# GEMM phase prologue de-serialisation: K-tile-1 staging loads issued together with the K-tile-0 loads (the first wait+barrier pair moved below them, vmcnt(2) -> vmcnt(8))
# baseline (speedup 1.0000x reference)
.LBB0_762:
	v_lshrrev_b32_e32 v15, 1, v172
	v_and_b32_e32 v15, 24, v15
	v_readlane_b32 s12, v251, 22
	v_and_b32_e32 v14, 15, v172
	v_lshlrev_b32_e32 v16, 1, v15
	v_readlane_b32 s13, v251, 23
	s_add_u32 s8, s12, 0x38c00000
	v_lshl_or_b32 v144, s11, 6, v14
	v_lshl_or_b32 v14, v14, 6, v16
	v_lshlrev_b32_e32 v16, 2, v172
	s_sext_i32_i8 s1, s4
	s_addc_u32 s9, s13, 0
	s_lshl_b32 s4, s11, 13
	v_and_b32_e32 v16, 32, v16
	v_bitop3_b32 v17, v14, s4, v16 bitop3:0xde
	s_lshl_b32 s4, s10, 5
	s_and_b32 s33, s4, 0x60
	s_add_i32 m0, s28, 0x18000
	v_lshl_add_u64 v[6:7], v[6:7], 0, s[90:91]
	s_lshl_b32 s10, s33, 7
	global_load_lds_dwordx4 v[6:7], off
	v_lshl_add_u64 v[4:5], v[4:5], 0, s[90:91]
	s_add_i32 m0, s28, 0x1a000
	s_add_i32 s34, s28, 0x8000
	s_add_i32 s35, s28, 0xa000
	v_bitop3_b32 v145, s10, v14, v16 bitop3:0xf6
	global_load_lds_dwordx4 v[4:5], off
	v_lshl_add_u64 v[0:1], v[0:1], 0, s[90:91]
	s_mov_b32 m0, s34
	s_add_u32 s10, s20, 0x40080
	global_load_lds_dwordx4 v[0:1], off
	v_lshl_add_u64 v[0:1], v[2:3], 0, s[90:91]
	s_mov_b32 m0, s35
	s_addc_u32 s11, s21, 0
	global_load_lds_dwordx4 v[0:1], off
	s_add_i32 m0, s28, 0x1c000
	v_lshl_add_u64 v[0:1], s[10:11], 0, v[96:97]
	global_load_lds_dwordx4 v[0:1], off
	v_lshl_add_u64 v[0:1], s[10:11], 0, v[130:131]
	s_add_i32 m0, s28, 0x1e000
	s_cmpk_lt_u32 s5, 0x100
	global_load_lds_dwordx4 v[0:1], off
	v_and_or_b32 v0, s4, 32, v15
	v_readlane_b32 s4, v251, 15
	v_lshlrev_b32_e32 v0, 1, v0
	v_mov_b32_e32 v1, v97
	s_cselect_b64 s[10:11], -1, 0
	s_ashr_i32 s36, s4, 31
	v_lshl_add_u64 v[0:1], s[12:13], 0, v[0:1]
	s_mov_b64 s[4:5], 0x24000000
	v_lshl_add_u64 v[136:137], v[0:1], 0, s[4:5]
	v_lshlrev_b32_e32 v0, 14, v12
	v_and_b32_e32 v0, 0xffff8000, v0
	v_lshl_add_u32 v0, v11, 11, v0
	v_and_b32_e32 v1, 1, v12
	v_lshl_or_b32 v0, v1, 6, v0
	v_lshl_add_u32 v138, v13, 1, v0
	v_lshlrev_b32_e32 v0, 14, v8
	v_and_b32_e32 v0, 0xffff8000, v0
	s_waitcnt vmcnt(8)
	s_barrier
	s_waitcnt vmcnt(6)
	v_lshl_add_u32 v0, v9, 11, v0
	v_and_b32_e32 v1, 1, v8
	v_lshl_or_b32 v0, v1, 6, v0
	v_mov_b32_e32 v139, v97
	v_lshl_add_u32 v140, v10, 1, v0
	v_mov_b32_e32 v141, v97
	s_mov_b32 s37, 0
	v_add_u32_e32 v146, 0, v17
	s_barrier
	s_branch .LBB0_765

.LBB0_789:
	v_readlane_b32 s8, v251, 22
	v_readlane_b32 s9, v251, 23
	s_add_u32 s14, s8, 0x38800000
	s_addc_u32 s15, s9, 0
	s_and_b32 s1, s5, 3
	s_add_i32 m0, s35, 0x18000
	v_lshl_add_u64 v[6:7], v[6:7], 0, s[90:91]
	s_lshl_b32 s5, s6, 13
	s_lshl_b32 s7, s1, 12
	global_load_lds_dwordx4 v[6:7], off
	v_lshl_add_u64 v[4:5], v[4:5], 0, s[90:91]
	s_add_i32 m0, s35, 0x1a000
	s_add_i32 s39, s35, 0x8000
	s_add_i32 s40, s35, 0xa000
	global_load_lds_dwordx4 v[4:5], off
	v_lshl_add_u64 v[0:1], v[0:1], 0, s[90:91]
	s_mov_b32 m0, s39
	s_add_u32 s8, s26, 0x40080
	global_load_lds_dwordx4 v[0:1], off
	v_lshl_add_u64 v[0:1], v[2:3], 0, s[90:91]
	s_mov_b32 m0, s40
	s_addc_u32 s9, s27, 0
	global_load_lds_dwordx4 v[0:1], off
	s_add_i32 m0, s35, 0x1c000
	v_lshl_add_u64 v[0:1], s[8:9], 0, v[96:97]
	global_load_lds_dwordx4 v[0:1], off
	v_lshl_add_u64 v[0:1], s[8:9], 0, v[130:131]
	s_add_i32 m0, s35, 0x1e000
	s_cmpk_lt_u32 s4, 0x100
	global_load_lds_dwordx4 v[0:1], off
	v_bfe_u32 v1, v172, 4, 2
	v_and_b32_e32 v0, 15, v172
	v_lshlrev_b32_e32 v2, 4, v1
	v_lshl_or_b32 v143, s6, 6, v0
	v_lshl_or_b32 v0, v0, 6, v2
	v_lshlrev_b32_e32 v2, 2, v172
	v_and_b32_e32 v2, 32, v2
	v_bitop3_b32 v3, v0, s5, v2 bitop3:0xde
	v_bitop3_b32 v144, s7, v0, v2 bitop3:0xf6
	v_lshlrev_b32_e32 v0, 2, v1
	v_lshl_or_b32 v145, s1, 5, v0
	v_lshlrev_b32_e32 v0, 14, v8
	v_and_b32_e32 v0, 0xffff8000, v0
	v_cmp_eq_u32_e64 s[4:5], 0, v1
	v_lshl_add_u32 v0, v9, 11, v0
	v_and_b32_e32 v1, 1, v8
	v_lshl_or_b32 v0, v1, 6, v0
	s_cselect_b64 s[16:17], -1, 0
	s_lshl_b32 s1, s1, 2
	v_lshl_add_u32 v132, v10, 1, v0
	v_lshlrev_b32_e32 v0, 14, v11
	s_add_i32 s1, s1, 0
	v_and_b32_e32 v0, 0xffff8000, v0
	s_waitcnt vmcnt(8)
	s_barrier
	s_waitcnt vmcnt(6)
	v_readlane_b32 s6, v251, 15
	s_add_i32 s1, s1, 0x20000
	v_lshl_add_u32 v0, v12, 11, v0
	v_and_b32_e32 v1, 1, v11
	s_ashr_i32 s42, s6, 31
	v_readlane_b32 s6, v251, 16
	v_lshl_add_u32 v146, v143, 4, s1
	s_movk_i32 s1, 0x100
	v_lshl_or_b32 v0, v1, 6, v0
	s_mov_b32 s41, 0
	s_ashr_i32 s43, s6, 31
	v_cmp_gt_i32_e64 s[6:7], s1, v172
	v_mov_b32_e32 v133, v97
	v_lshl_add_u32 v134, v13, 1, v0
	v_mov_b32_e32 v135, v97
	v_add_u32_e32 v147, 0, v3
	s_barrier
	s_branch .LBB0_793

.LBB0_934:
	v_readlane_b32 s10, v251, 22
	v_readlane_b32 s11, v251, 23
	s_add_u32 s4, s10, s4
	s_addc_u32 s5, s11, s5
	s_add_u32 s22, s4, 0x38000000
	s_addc_u32 s23, s5, 0
	v_readlane_b32 s4, v251, 29
	s_cmp_lg_u32 s4, 2
	s_cselect_b64 s[4:5], -1, 0
	s_cmp_lg_u32 s34, 3
	s_cselect_b64 s[10:11], -1, 0
	s_or_b64 s[24:25], s[4:5], s[10:11]
	s_xor_b64 s[26:27], s[24:25], -1
	s_and_b32 s8, s8, 3
	v_bfe_u32 v8, v172, 4, 2
	s_lshr_b32 s47, s7, 6
	v_and_b32_e32 v9, 15, v172
	s_and_b64 s[4:5], s[12:13], exec
	v_lshlrev_b32_e32 v10, 4, v8
	s_mov_b32 s4, 0x8000
	v_lshl_or_b32 v173, s9, 6, v9
	v_lshl_or_b32 v9, v9, 6, v10
	v_lshlrev_b32_e32 v10, 2, v172
	s_cselect_b32 s50, 0x80, s4
	s_lshl_b32 s4, s9, 13
	v_and_b32_e32 v10, 32, v10
	s_add_i32 m0, s43, 0x18000
	v_lshl_add_u64 v[0:1], v[0:1], 0, s[90:91]
	v_bitop3_b32 v11, v9, s4, v10 bitop3:0xde
	s_lshl_b32 s4, s8, 12
	global_load_lds_dwordx4 v[0:1], off
	s_add_i32 m0, s43, 0x1a000
	v_bitop3_b32 v190, s4, v9, v10 bitop3:0xf6
	s_add_u32 s4, s0, s50
	v_mov_b32_e32 v131, v97
	v_lshl_add_u64 v[0:1], v[2:3], 0, s[90:91]
	s_addc_u32 s5, s1, 0
	s_add_i32 s52, s43, 0x8000
	v_mov_b32_e32 v133, v97
	global_load_lds_dwordx4 v[0:1], off
	v_lshl_add_u64 v[0:1], s[4:5], 0, v[130:131]
	s_mov_b32 m0, s52
	s_add_i32 s53, s43, 0xa000
	global_load_lds_dwordx4 v[0:1], off
	v_lshl_add_u64 v[0:1], s[4:5], 0, v[132:133]
	s_mov_b32 m0, s53
	s_mov_b32 s51, 0
	global_load_lds_dwordx4 v[0:1], off
	s_add_i32 m0, s43, 0x1c000
	v_lshl_add_u64 v[0:1], v[4:5], 0, s[90:91]
	global_load_lds_dwordx4 v[0:1], off
	v_lshl_add_u64 v[0:1], v[6:7], 0, s[90:91]
	s_add_i32 m0, s43, 0x1e000
	s_and_b64 s[4:5], s[12:13], exec
	global_load_lds_dwordx4 v[0:1], off
	s_cselect_b32 s54, 7, 15
	s_cmpk_lt_u32 s6, 0x100
	v_readlane_b32 s6, v251, 15
	s_cselect_b64 s[28:29], -1, 0
	s_ashr_i32 s55, s6, 31
	v_readlane_b32 s6, v251, 16
	s_ashr_i32 s56, s6, 31
	v_readlane_b32 s6, v251, 11
	s_lshr_b32 s57, s6, 3
	s_lshl_b32 s6, s8, 2
	s_add_i32 s6, s6, 0
	s_waitcnt vmcnt(8)
	s_barrier
	s_waitcnt vmcnt(6)
	s_add_i32 s6, s6, 0x20000
	v_lshlrev_b32_e32 v0, 2, v8
	v_readlane_b32 s7, v251, 12
	v_lshl_add_u32 v192, v173, 4, s6
	s_movk_i32 s6, 0x100
	v_lshl_or_b32 v191, s8, 5, v0
	v_cmp_eq_u32_e64 s[4:5], 0, v8
	v_cmp_gt_i32_e64 s[6:7], s6, v172
	s_mov_b32 s15, s14
	s_add_u32 s58, s47, -2
	v_add_u32_e32 v193, 0, v11
	s_barrier
	s_branch .LBB0_937

.LBB0_1125:
	s_sext_i32_i16 s1, s8
	v_readlane_b32 s8, v251, 22
	v_readlane_b32 s9, v251, 23
	s_add_u32 s4, s8, s4
	s_addc_u32 s5, s9, s5
	s_add_u32 s8, s4, 0x38000000
	s_addc_u32 s9, s5, 0
	s_and_b32 s4, s12, 3
	v_and_b32_e32 v15, 15, v172
	v_and_b32_e32 v14, 48, v172
	v_lshlrev_b32_e32 v16, 2, v172
	s_add_i32 m0, s29, 0x18000
	v_lshl_add_u64 v[6:7], v[6:7], 0, s[90:91]
	v_lshl_or_b32 v148, s11, 6, v15
	v_lshl_or_b32 v15, v15, 6, v14
	s_lshl_b32 s5, s11, 13
	v_and_b32_e32 v16, 32, v16
	s_lshl_b32 s4, s4, 12
	global_load_lds_dwordx4 v[6:7], off
	v_lshl_add_u64 v[4:5], v[4:5], 0, s[90:91]
	s_add_i32 m0, s29, 0x1a000
	s_add_i32 s34, s29, 0x8000
	s_add_i32 s35, s29, 0xa000
	v_bitop3_b32 v169, s4, v15, v16 bitop3:0xf6
	global_load_lds_dwordx4 v[4:5], off
	v_lshl_add_u64 v[0:1], v[0:1], 0, s[90:91]
	s_mov_b32 m0, s34
	s_add_u32 s4, s20, 0x40080
	v_bitop3_b32 v17, v15, s5, v16 bitop3:0xde
	global_load_lds_dwordx4 v[0:1], off
	v_lshl_add_u64 v[0:1], v[2:3], 0, s[90:91]
	s_mov_b32 m0, s35
	s_addc_u32 s5, s21, 0
	global_load_lds_dwordx4 v[0:1], off
	s_add_i32 m0, s29, 0x1c000
	v_lshl_add_u64 v[0:1], s[4:5], 0, v[96:97]
	global_load_lds_dwordx4 v[0:1], off
	v_lshl_add_u64 v[0:1], s[4:5], 0, v[142:143]
	s_add_i32 m0, s29, 0x1e000
	v_ashrrev_i32_e32 v149, 31, v148
	global_load_lds_dwordx4 v[0:1], off
	v_or_b32_e32 v0, 16, v148
	v_ashrrev_i32_e32 v1, 31, v0
	v_lshlrev_b64 v[152:153], 7, v[0:1]
	v_or_b32_e32 v0, 32, v148
	v_ashrrev_i32_e32 v1, 31, v0
	v_lshlrev_b64 v[154:155], 7, v[0:1]
	v_or_b32_e32 v0, 48, v148
	v_lshlrev_b64 v[150:151], 7, v[148:149]
	v_ashrrev_i32_e32 v1, 31, v0
	s_mov_b64 s[4:5], 0x4000
	v_lshlrev_b64 v[156:157], 7, v[0:1]
	v_lshl_add_u64 v[158:159], v[150:151], 0, s[4:5]
	s_mov_b64 s[4:5], 0x4800
	v_lshlrev_b32_e32 v0, 14, v12
	v_lshl_add_u64 v[160:161], v[150:151], 0, s[4:5]
	s_mov_b64 s[4:5], 0x5000
	v_and_b32_e32 v0, 0xffff8000, v0
	v_lshl_add_u64 v[162:163], v[150:151], 0, s[4:5]
	s_mov_b64 s[4:5], 0x5800
	v_lshl_add_u32 v0, v11, 11, v0
	v_and_b32_e32 v1, 1, v12
	s_cmpk_lt_u32 s10, 0x100
	v_lshl_add_u64 v[164:165], v[150:151], 0, s[4:5]
	v_readlane_b32 s4, v251, 15
	v_lshl_or_b32 v0, v1, 6, v0
	s_cselect_b64 s[10:11], -1, 0
	s_ashr_i32 s37, s4, 31
	s_lshl_b32 s4, s12, 6
	v_lshl_add_u32 v174, v13, 1, v0
	v_lshlrev_b32_e32 v0, 14, v8
	s_bfe_u32 s36, s12, 0x10001
	s_and_b32 s4, s4, 64
	v_readlane_b32 s12, v251, 24
	v_and_b32_e32 v0, 0xffff8000, v0
	s_waitcnt vmcnt(8)
	s_barrier
	s_waitcnt vmcnt(6)
	v_readlane_b32 s13, v251, 25
	s_add_u32 s4, s12, s4
	v_lshl_add_u32 v0, v9, 11, v0
	v_and_b32_e32 v1, 1, v8
	s_addc_u32 s5, s13, 0
	v_mov_b32_e32 v15, v97
	v_lshl_or_b32 v0, v1, 6, v0
	v_lshl_add_u64 v[166:167], s[4:5], 0, v[14:15]
	v_mov_b32_e32 v175, v97
	v_lshl_add_u32 v176, v10, 1, v0
	v_mov_b32_e32 v177, v97
	s_mov_b32 s38, 0
	v_add_u32_e32 v149, 0, v17
	s_barrier
	s_branch .LBB0_1128
